# phase-2 pooling differences: interior waves use an 8-token dwordx4 fast path (all window loads of a pass in flight, immediate offsets, no exec masking); boundary tokens keep the original loop
# speedup vs baseline: 1.0090x; 1.0090x over previous
; __device__ __forceinline__ unsigned cvt_pk_bf16(float lo, float hi) { unsigned r; asm volatile("v_cvt_pk_bf16_f32 %0, %1, %2" : "=v"(r) : "v"(lo), "v"(hi)); return r; }
; #define LAS __attribute__((address_space(3)))
; __device__ __forceinline__ int crow(int r, int hi) { return (r & 3) + 8 * (r >> 2) + 4 * hi; }
; template <bool MERGE> __device__ __forceinline__ void compute_b(LAS unsigned char* lds, const UD& x, unsigned char* ws, unsigned char* dout, int wid, int lane, const u32x4 (&pw)[10], float mx, float lsum) {
;     ...
;     asm volatile("s_waitcnt lgkmcnt(0)" ::: "memory");
; #pragma unroll
;     for (int r = 0; r < 16; ++r) {
;         const int qrow = crow(r, hi); const float rl = __builtin_amdgcn_rcpf(wsf[qrow]);
;         const unsigned a = pg8::cvt_pk_bf16(o[0][r] * rl, o[1][r] * rl);
;         stg[qrow * 64 + r32] = (bf16_t)(a & 0xffffu); stg[qrow * 64 + 32 + r32] = (bf16_t)(a >> 16);
;     }
;     asm volatile("s_waitcnt lgkmcnt(0)" ::: "memory");
;     if (!MERGE) {
;         bf16_t* Ob = o_base(ws, dout, x.br, x.b);
; #pragma unroll
;         for (int i = 0; i < 4; ++i) {
;             const int row = i * 8 + (lane >> 3), ch = lane & 7;
;             const u32x4 v = *(const LAS u32x4*)(stg + row * 64 + ch * 8);
;             *(u32x4*)(Ob + (tokb + (size_t)(t0 + row) * d + cls) * AW + x.h * HD + ch * 8) = v;
;         }
;     } else {
;         const float* ST = (const float*)(ws + WS_STAT); bf16_t* MIX = (bf16_t*)(ws + WS_MIXN);
; #pragma unroll
;         for (int i0 = 0; i0 < 4; i0 += 2) {
;             u32x4 o1[2], o2[2]; float m1[2], l1[2], m2[2], l2[2];
; #pragma unroll
;             for (int ii = 0; ii < 2; ++ii) {
;                 const int row = (i0 + ii) * 8 + (lane >> 3), ch = lane & 7; const size_t tok = tokb + (size_t)(t0 + row);
;                 const float* s1 = ST + (((size_t)1 * M + tok) * NH + x.h) * 2; const float* s2 = ST + (((size_t)2 * M + tok) * NH + x.h) * 2;
;                 m1[ii] = s1[0]; l1[ii] = s1[1]; m2[ii] = s2[0]; l2[ii] = s2[1];
;                 o1[ii] = *(const u32x4*)(o_base(ws, dout, 1, x.b) + tok * AW + x.h * HD + ch * 8); o2[ii] = *(const u32x4*)(o_base(ws, dout, 2, x.b) + tok * AW + x.h * HD + ch * 8);
;             }
.LBB0_940:
	s_or_b64 exec, exec, s[18:19]
	s_waitcnt lgkmcnt(0)
	ds_read_b32 v32, v162
	ds_read_b32 v33, v162 offset:4
	ds_read_b32 v34, v162 offset:8
	ds_read_b32 v35, v162 offset:12
	ds_read_b32 v36, v162 offset:32
	ds_read_b32 v37, v162 offset:36
	ds_read_b32 v38, v162 offset:40
	ds_read_b32 v39, v162 offset:44
	ds_read_b32 v40, v162 offset:64
	ds_read_b32 v41, v162 offset:68
	ds_read_b32 v42, v162 offset:72
	ds_read_b32 v43, v162 offset:76
	ds_read_b32 v44, v162 offset:96
	ds_read_b32 v45, v162 offset:100
	ds_read_b32 v46, v162 offset:104
	ds_read_b32 v47, v162 offset:108
	s_waitcnt lgkmcnt(0)
	s_ashr_i32 s19, s22, 31
	s_mul_i32 s24, s0, 0x500000
	v_readlane_b32 s46, v254, 59
	s_mul_hi_i32 s23, s0, 0x500000
	v_rcp_f32_e32 v32, v32
	v_readlane_b32 s47, v254, 60
	v_mov_b32_e32 v145, v81
	v_mul_f32_e32 v0, v0, v32
	v_mul_f32_e32 v16, v16, v32
	v_cvt_pk_bf16_f32 v0, v0, v16
	ds_write_b16 v163, v0
	ds_write_b16_d16_hi v164, v0
	v_rcp_f32_e32 v0, v33
	s_nop 0
	v_mul_f32_e32 v1, v1, v0
	v_mul_f32_e32 v0, v17, v0
	v_cvt_pk_bf16_f32 v0, v1, v0
	ds_write_b16 v165, v0
	ds_write_b16_d16_hi v166, v0
	v_rcp_f32_e32 v0, v34
	s_nop 0
	v_mul_f32_e32 v1, v2, v0
	v_mul_f32_e32 v0, v18, v0
	v_cvt_pk_bf16_f32 v0, v1, v0
	ds_write_b16 v167, v0
	ds_write_b16_d16_hi v168, v0
	v_rcp_f32_e32 v0, v35
	s_nop 0
	v_mul_f32_e32 v1, v3, v0
	v_mul_f32_e32 v0, v19, v0
	v_cvt_pk_bf16_f32 v0, v1, v0
	ds_write_b16 v169, v0
	ds_write_b16_d16_hi v170, v0
	v_rcp_f32_e32 v0, v36
	s_nop 0
	v_mul_f32_e32 v1, v4, v0
	v_mul_f32_e32 v0, v20, v0
	v_cvt_pk_bf16_f32 v0, v1, v0
	ds_write_b16 v171, v0
	ds_write_b16_d16_hi v172, v0
	v_rcp_f32_e32 v0, v37
	s_nop 0
	v_mul_f32_e32 v1, v5, v0
	v_mul_f32_e32 v0, v21, v0
	v_cvt_pk_bf16_f32 v0, v1, v0
	ds_write_b16 v173, v0
	ds_write_b16_d16_hi v174, v0
	v_rcp_f32_e32 v0, v38
	s_nop 0
	v_mul_f32_e32 v1, v6, v0
	v_mul_f32_e32 v0, v22, v0
	v_cvt_pk_bf16_f32 v0, v1, v0
	ds_write_b16 v175, v0
	ds_write_b16_d16_hi v176, v0
	v_rcp_f32_e32 v0, v39
	s_nop 0
	v_mul_f32_e32 v1, v7, v0
	v_mul_f32_e32 v0, v23, v0
	v_cvt_pk_bf16_f32 v0, v1, v0
	ds_write_b16 v177, v0
	ds_write_b16_d16_hi v178, v0
	v_rcp_f32_e32 v0, v40
	s_nop 0
	v_mul_f32_e32 v1, v8, v0
	v_mul_f32_e32 v0, v24, v0
	v_cvt_pk_bf16_f32 v0, v1, v0
	ds_write_b16 v179, v0
	ds_write_b16_d16_hi v180, v0
	v_rcp_f32_e32 v0, v41
	s_nop 0
	v_mul_f32_e32 v1, v9, v0
	v_mul_f32_e32 v0, v25, v0
	v_cvt_pk_bf16_f32 v0, v1, v0
	ds_write_b16 v181, v0
	ds_write_b16_d16_hi v182, v0
	v_rcp_f32_e32 v0, v42
	s_nop 0
	v_mul_f32_e32 v1, v10, v0
	v_mul_f32_e32 v0, v26, v0
	v_cvt_pk_bf16_f32 v0, v1, v0
	ds_write_b16 v183, v0
	ds_write_b16_d16_hi v184, v0
	v_rcp_f32_e32 v0, v43
	s_nop 0
	v_mul_f32_e32 v1, v11, v0
	v_mul_f32_e32 v0, v27, v0
	v_cvt_pk_bf16_f32 v0, v1, v0
	ds_write_b16 v185, v0
	ds_write_b16_d16_hi v186, v0
	v_rcp_f32_e32 v0, v44
	s_nop 0
	v_mul_f32_e32 v1, v12, v0
	v_mul_f32_e32 v0, v28, v0
	v_cvt_pk_bf16_f32 v0, v1, v0
	ds_write_b16 v187, v0
	ds_write_b16_d16_hi v188, v0
	v_rcp_f32_e32 v0, v45
	s_nop 0
	v_mul_f32_e32 v1, v13, v0
	v_mul_f32_e32 v0, v29, v0
	v_cvt_pk_bf16_f32 v0, v1, v0
	ds_write_b16 v189, v0
	ds_write_b16_d16_hi v202, v0
	v_rcp_f32_e32 v0, v46
	s_nop 0
	v_mul_f32_e32 v1, v14, v0
	v_mul_f32_e32 v0, v30, v0
	v_cvt_pk_bf16_f32 v0, v1, v0
	ds_write_b16 v203, v0
	ds_write_b16_d16_hi v204, v0
	v_or_b32_e32 v14, s20, v207
	s_add_u32 s20, s22, 0x30000
	s_addc_u32 s21, s19, 0
	s_add_u32 s18, s22, 0x60000
	v_rcp_f32_e32 v0, v47
	s_addc_u32 s19, s19, 0
	s_lshl_b64 s[16:17], s[16:17], 1
	s_add_u32 s24, s46, s24
	s_addc_u32 s23, s47, s23
	v_mul_f32_e32 v1, v15, v0
	v_mul_f32_e32 v0, v31, v0
	s_add_u32 s24, s24, s16
	v_ashrrev_i32_e32 v15, 31, v14
	v_cvt_pk_bf16_f32 v0, v1, v0
	s_addc_u32 s25, s23, s17
	v_lshl_add_u64 v[24:25], s[14:15], 0, v[14:15]
	ds_write_b16 v205, v0
	ds_write_b16_d16_hi v206, v0
	v_lshl_add_u64 v[16:17], s[24:25], 0, v[144:145]
	v_mad_u64_u32 v[0:1], s[24:25], v24, 12, s[20:21]
	v_mad_i32_i24 v1, v25, 12, v1
	v_mad_u64_u32 v[2:3], s[24:25], v24, 12, s[18:19]
	s_waitcnt lgkmcnt(0)
	v_lshl_add_u64 v[0:1], v[0:1], 3, s[34:35]
	v_mad_i32_i24 v3, v25, 12, v3
	v_lshl_add_u64 v[2:3], v[2:3], 3, s[34:35]
	global_load_dwordx2 v[34:35], v[0:1], off
	global_load_dwordx2 v[36:37], v[2:3], off
	v_lshl_add_u64 v[12:13], v[136:137], 0, s[16:17]
	v_mad_u64_u32 v[0:1], s[24:25], v24, s40, v[12:13]
	v_mad_i32_i24 v1, v25, s40, v1
	global_load_dwordx4 v[8:11], v[0:1], off
	v_mad_u64_u32 v[0:1], s[24:25], v24, s40, v[16:17]
	v_mad_i32_i24 v1, v25, s40, v1
	global_load_dwordx4 v[26:29], v[0:1], off
	v_or_b32_e32 v0, 8, v14
	v_ashrrev_i32_e32 v1, 31, v0
	v_lshl_add_u64 v[18:19], s[14:15], 0, v[0:1]
	v_mad_u64_u32 v[0:1], s[24:25], v18, 12, s[20:21]
	v_mad_i32_i24 v1, v19, 12, v1
	v_mad_u64_u32 v[2:3], s[24:25], v18, 12, s[18:19]
	v_lshl_add_u64 v[0:1], v[0:1], 3, s[34:35]
	v_mad_i32_i24 v3, v19, 12, v3
	v_lshl_add_u64 v[2:3], v[2:3], 3, s[34:35]
	global_load_dwordx2 v[20:21], v[0:1], off
	global_load_dwordx2 v[22:23], v[2:3], off
	v_mad_u64_u32 v[0:1], s[24:25], v18, s40, v[12:13]
	v_mad_i32_i24 v1, v19, s40, v1
	global_load_dwordx4 v[0:3], v[0:1], off
	v_mad_u64_u32 v[4:5], s[24:25], v18, s40, v[16:17]
	v_mad_i32_i24 v5, v19, s40, v5
	global_load_dwordx4 v[4:7], v[4:5], off
	v_add_u32_e32 v15, v208, v209
	ds_read_b128 v[30:33], v15
	ds_read2_b32 v[38:39], v210 offset1:32
	v_lshlrev_b64 v[24:25], 11, v[24:25]
	v_lshl_add_u64 v[24:25], s[84:85], 0, v[24:25]
	v_lshl_add_u64 v[24:25], v[24:25], 0, s[16:17]
	v_lshl_add_u64 v[24:25], v[24:25], 0, v[144:145]
	s_cmp_gt_i32 s22, 3
	s_waitcnt vmcnt(6) lgkmcnt(0)
; __device__ __forceinline__ unsigned cvt_pk_bf16(float lo, float hi) { unsigned r; asm volatile("v_cvt_pk_bf16_f32 %0, %1, %2" : "=v"(r) : "v"(lo), "v"(hi)); return r; }
; #define LAS __attribute__((address_space(3)))
; template <bool MERGE> __device__ __forceinline__ void compute_b(LAS unsigned char* lds, const UD& x, unsigned char* ws, unsigned char* dout, int wid, int lane, const u32x4 (&pw)[10], float mx, float lsum) {
;     ...
; #pragma unroll
;             for (int ii = 0; ii < 2; ++ii) {
;                 const int row = (i0 + ii) * 8 + (lane >> 3), ch = lane & 7; const size_t tok = tokb + (size_t)(t0 + row);
;                 const u32x4 v0 = *(const LAS u32x4*)(stg + row * 64 + ch * 8);
;                 const float m0 = wsf[32 + row], l0 = wsf[row];
;                 const float mxx = fmaxf(fmaxf(m0, m1[ii]), m2[ii]);
;                 float w0 = __builtin_amdgcn_exp2f(m0 - mxx) * l0, w1 = __builtin_amdgcn_exp2f(m1[ii] - mxx) * l1[ii], w2 = __builtin_amdgcn_exp2f(m2[ii] - mxx) * l2[ii];
;                 const float rd = 1.0f / (w0 + w1 + w2); w0 *= rd; w1 *= rd; w2 *= rd;
;                 const u32x4 a1 = o1[ii], a2 = o2[ii];
;                 u32x4 w;
;                 w.x = pg8::cvt_pk_bf16(w0 * __uint_as_float(v0.x << 16) + w1 * __uint_as_float(a1.x << 16) + w2 * __uint_as_float(a2.x << 16), w0 * __uint_as_float(v0.x & 0xffff0000u) + w1 * __uint_as_float(a1.x & 0xffff0000u) + w2 * __uint_as_float(a2.x & 0xffff0000u));
;                 w.y = pg8::cvt_pk_bf16(w0 * __uint_as_float(v0.y << 16) + w1 * __uint_as_float(a1.y << 16) + w2 * __uint_as_float(a2.y << 16), w0 * __uint_as_float(v0.y & 0xffff0000u) + w1 * __uint_as_float(a1.y & 0xffff0000u) + w2 * __uint_as_float(a2.y & 0xffff0000u));
;                 w.z = pg8::cvt_pk_bf16(w0 * __uint_as_float(v0.z << 16) + w1 * __uint_as_float(a1.z << 16) + w2 * __uint_as_float(a2.z << 16), w0 * __uint_as_float(v0.z & 0xffff0000u) + w1 * __uint_as_float(a1.z & 0xffff0000u) + w2 * __uint_as_float(a2.z & 0xffff0000u));
;                 w.w = pg8::cvt_pk_bf16(w0 * __uint_as_float(v0.w << 16) + w1 * __uint_as_float(a1.w << 16) + w2 * __uint_as_float(a2.w << 16), w0 * __uint_as_float(v0.w & 0xffff0000u) + w1 * __uint_as_float(a1.w & 0xffff0000u) + w2 * __uint_as_float(a2.w & 0xffff0000u));
;                 *(u32x4*)(MIX + tok * DM + PWD + x.h * HD + ch * 8) = w;
;             }
;         }
	v_max3_f32 v15, v39, v34, v36
	v_sub_f32_e32 v39, v39, v15
	v_sub_f32_e32 v34, v34, v15
	v_sub_f32_e32 v15, v36, v15
	v_exp_f32_e32 v41, v39
	v_exp_f32_e32 v40, v15
	v_exp_f32_e32 v34, v34
	s_waitcnt vmcnt(5)
	v_lshlrev_b32_e32 v15, 16, v8
	v_and_b32_e32 v36, 0xffff0000, v8
	v_lshlrev_b32_e32 v42, 16, v9
	v_and_b32_e32 v43, 0xffff0000, v9
	v_mov_b32_e32 v8, v37
	v_mov_b32_e32 v9, v38
	v_pk_mul_f32 v[8:9], v[8:9], v[40:41]
	v_lshlrev_b32_e32 v44, 16, v10
	v_and_b32_e32 v45, 0xffff0000, v10
	v_fma_f32 v10, v35, v34, v9
	v_add_f32_e32 v10, v8, v10
	v_mul_f32_e32 v39, v35, v34
	v_div_scale_f32 v34, s[24:25], v10, v10, 1.0
	v_rcp_f32_e32 v35, v34
	v_lshlrev_b32_e32 v46, 16, v11
	v_fma_f32 v37, -v34, v35, 1.0
	v_fmac_f32_e32 v35, v37, v35
	v_div_scale_f32 v37, vcc, 1.0, v10, 1.0
	v_mul_f32_e32 v38, v37, v35
	v_fma_f32 v40, -v34, v38, v37
	v_fmac_f32_e32 v38, v40, v35
	v_fma_f32 v34, -v34, v38, v37
	v_div_fmas_f32 v34, v34, v35, v38
	v_div_fixup_f32 v10, v34, v10, 1.0
	v_pk_mul_f32 v[34:35], v[8:9], v[10:11] op_sel_hi:[1,0]
	s_waitcnt vmcnt(4)
	v_lshlrev_b32_e32 v8, 16, v26
	v_lshlrev_b32_e32 v9, 16, v30
	v_mul_f32_e32 v38, v39, v10
	v_pk_mul_f32 v[8:9], v[34:35], v[8:9]
	v_lshlrev_b32_e32 v37, 16, v31
	v_fma_f32 v9, v38, v15, v9
	v_add_f32_e32 v10, v8, v9
	v_and_b32_e32 v9, 0xffff0000, v30
	v_and_b32_e32 v8, 0xffff0000, v26
	v_pk_mul_f32 v[8:9], v[34:35], v[8:9]
	v_and_b32_e32 v31, 0xffff0000, v31
	v_fma_f32 v9, v38, v36, v9
	v_and_b32_e32 v30, 0xffff0000, v27
	v_add_f32_e32 v8, v8, v9
	v_lshlrev_b32_e32 v36, 16, v27
	v_pk_mul_f32 v[26:27], v[34:35], v[30:31]
	v_cvt_pk_bf16_f32 v8, v10, v8
	v_pk_mul_f32 v[36:37], v[34:35], v[36:37]
	v_fma_f32 v10, v38, v43, v27
	v_fma_f32 v9, v38, v42, v37
	v_add_f32_e32 v10, v26, v10
	v_lshlrev_b32_e32 v26, 16, v28
	v_lshlrev_b32_e32 v27, 16, v32
	v_add_f32_e32 v9, v36, v9
	v_pk_mul_f32 v[26:27], v[34:35], v[26:27]
	v_cvt_pk_bf16_f32 v9, v9, v10
	v_and_b32_e32 v11, 0xffff0000, v11
	v_fma_f32 v10, v38, v44, v27
	v_add_f32_e32 v10, v26, v10
	v_and_b32_e32 v27, 0xffff0000, v32
	v_and_b32_e32 v26, 0xffff0000, v28
	v_pk_mul_f32 v[26:27], v[34:35], v[26:27]
	s_waitcnt vmcnt(1)
	v_lshlrev_b32_e32 v28, 16, v1
	v_fma_f32 v15, v38, v45, v27
	v_add_f32_e32 v15, v26, v15
	v_lshlrev_b32_e32 v26, 16, v29
	v_lshlrev_b32_e32 v27, 16, v33
	v_pk_mul_f32 v[26:27], v[34:35], v[26:27]
	v_cvt_pk_bf16_f32 v10, v10, v15
	v_lshlrev_b32_e32 v30, 16, v2
	v_fma_f32 v15, v38, v46, v27
	v_add_f32_e32 v15, v26, v15
	v_and_b32_e32 v27, 0xffff0000, v33
	v_and_b32_e32 v26, 0xffff0000, v29
	v_pk_mul_f32 v[26:27], v[34:35], v[26:27]
	v_and_b32_e32 v29, 0xffff0000, v1
	v_fma_f32 v11, v38, v11, v27
	v_add_f32_e32 v11, v26, v11
	v_cvt_pk_bf16_f32 v11, v15, v11
	global_store_dwordx4 v[24:25], v[8:11], off offset:512
	ds_read_b128 v[8:11], v229
	ds_read2_b32 v[26:27], v210 offset0:8 offset1:40
	v_and_b32_e32 v31, 0xffff0000, v2
	v_lshlrev_b32_e32 v32, 16, v3
	s_waitcnt lgkmcnt(0)
	v_max3_f32 v15, v27, v20, v22
	v_sub_f32_e32 v24, v27, v15
	v_sub_f32_e32 v20, v20, v15
	v_sub_f32_e32 v15, v22, v15
	v_exp_f32_e32 v25, v24
	v_exp_f32_e32 v24, v15
	v_exp_f32_e32 v20, v20
	v_lshlrev_b32_e32 v15, 16, v0
	v_and_b32_e32 v22, 0xffff0000, v0
	v_mov_b32_e32 v0, v23
	v_mov_b32_e32 v1, v26
	v_pk_mul_f32 v[0:1], v[0:1], v[24:25]
	v_mul_f32_e32 v27, v21, v20
	v_fma_f32 v2, v21, v20, v1
	v_add_f32_e32 v2, v0, v2
	v_div_scale_f32 v20, s[24:25], v2, v2, 1.0
	v_rcp_f32_e32 v21, v20
	s_nop 0
	v_fma_f32 v23, -v20, v21, 1.0
	v_fmac_f32_e32 v21, v23, v21
	v_div_scale_f32 v23, vcc, 1.0, v2, 1.0
	v_mul_f32_e32 v24, v23, v21
	v_fma_f32 v25, -v20, v24, v23
	v_fmac_f32_e32 v24, v25, v21
	v_fma_f32 v20, -v20, v24, v23
	v_div_fmas_f32 v20, v20, v21, v24
	v_div_fixup_f32 v2, v20, v2, 1.0
	v_pk_mul_f32 v[20:21], v[0:1], v[2:3] op_sel_hi:[1,0]
	s_waitcnt vmcnt(1)
	v_lshlrev_b32_e32 v0, 16, v4
	v_lshlrev_b32_e32 v1, 16, v8
	v_mul_f32_e32 v24, v27, v2
	v_pk_mul_f32 v[0:1], v[20:21], v[0:1]
	v_lshlrev_b32_e32 v23, 16, v9
	v_fma_f32 v1, v24, v15, v1
	v_add_f32_e32 v2, v0, v1
	v_and_b32_e32 v1, 0xffff0000, v8
	v_and_b32_e32 v0, 0xffff0000, v4
	v_pk_mul_f32 v[0:1], v[20:21], v[0:1]
	v_and_b32_e32 v9, 0xffff0000, v9
	v_fma_f32 v1, v24, v22, v1
	v_and_b32_e32 v8, 0xffff0000, v5
	v_add_f32_e32 v0, v0, v1
	v_lshlrev_b32_e32 v22, 16, v5
	v_pk_mul_f32 v[4:5], v[20:21], v[8:9]
	v_cvt_pk_bf16_f32 v0, v2, v0
	v_pk_mul_f32 v[22:23], v[20:21], v[22:23]
	v_fma_f32 v2, v24, v29, v5
	v_fma_f32 v1, v24, v28, v23
	v_add_f32_e32 v2, v4, v2
	v_lshlrev_b32_e32 v4, 16, v6
	v_lshlrev_b32_e32 v5, 16, v10
	v_add_f32_e32 v1, v22, v1
	v_pk_mul_f32 v[4:5], v[20:21], v[4:5]
	v_cvt_pk_bf16_f32 v1, v1, v2
	v_and_b32_e32 v3, 0xffff0000, v3
	v_fma_f32 v2, v24, v30, v5
	v_add_f32_e32 v2, v4, v2
	v_and_b32_e32 v5, 0xffff0000, v10
	v_and_b32_e32 v4, 0xffff0000, v6
	v_pk_mul_f32 v[4:5], v[20:21], v[4:5]
	s_nop 0
	v_fma_f32 v5, v24, v31, v5
	v_add_f32_e32 v4, v4, v5
	v_cvt_pk_bf16_f32 v2, v2, v4
	v_lshlrev_b32_e32 v4, 16, v7
	v_lshlrev_b32_e32 v5, 16, v11
	v_pk_mul_f32 v[4:5], v[20:21], v[4:5]
	s_nop 0
	v_fma_f32 v5, v24, v32, v5
	v_add_f32_e32 v6, v4, v5
	v_and_b32_e32 v5, 0xffff0000, v11
	v_and_b32_e32 v4, 0xffff0000, v7
	v_pk_mul_f32 v[4:5], v[20:21], v[4:5]
	s_nop 0
	v_fma_f32 v3, v24, v3, v5
	v_add_f32_e32 v3, v4, v3
	v_lshlrev_b64 v[4:5], 11, v[18:19]
	v_lshl_add_u64 v[4:5], s[84:85], 0, v[4:5]
	v_lshl_add_u64 v[4:5], v[4:5], 0, s[16:17]
	v_lshl_add_u64 v[4:5], v[4:5], 0, v[144:145]
	v_cvt_pk_bf16_f32 v3, v6, v3
	global_store_dwordx4 v[4:5], v[0:3], off offset:512
	s_nop 1
	v_or_b32_e32 v0, 16, v14
	v_ashrrev_i32_e32 v1, 31, v0
	v_lshl_add_u64 v[30:31], s[14:15], 0, v[0:1]
	v_mad_u64_u32 v[0:1], s[24:25], v30, 12, s[20:21]
	v_mad_i32_i24 v1, v31, 12, v1
	v_mad_u64_u32 v[2:3], s[24:25], v30, 12, s[18:19]
	v_lshl_add_u64 v[0:1], v[0:1], 3, s[34:35]
	v_mad_i32_i24 v3, v31, 12, v3
	v_lshl_add_u64 v[2:3], v[2:3], 3, s[34:35]
	global_load_dwordx2 v[32:33], v[0:1], off
	global_load_dwordx2 v[34:35], v[2:3], off
	v_mad_u64_u32 v[0:1], s[24:25], v30, s40, v[12:13]
	v_mad_i32_i24 v1, v31, s40, v1
	global_load_dwordx4 v[18:21], v[0:1], off
	v_mad_u64_u32 v[0:1], s[24:25], v30, s40, v[16:17]
	v_mad_i32_i24 v1, v31, s40, v1
	global_load_dwordx4 v[22:25], v[0:1], off
	v_or_b32_e32 v0, 24, v14
	v_ashrrev_i32_e32 v1, 31, v0
	v_lshl_add_u64 v[8:9], s[14:15], 0, v[0:1]
	v_mad_u64_u32 v[0:1], s[14:15], v8, 12, s[20:21]
	v_mad_i32_i24 v1, v9, 12, v1
	v_mad_u64_u32 v[2:3], s[14:15], v8, 12, s[18:19]
	v_lshl_add_u64 v[0:1], v[0:1], 3, s[34:35]
	v_mad_i32_i24 v3, v9, 12, v3
	v_lshl_add_u64 v[2:3], v[2:3], 3, s[34:35]
	global_load_dwordx2 v[10:11], v[0:1], off
	global_load_dwordx2 v[14:15], v[2:3], off
	v_mad_u64_u32 v[0:1], s[14:15], v8, s40, v[12:13]
	v_mad_i32_i24 v1, v9, s40, v1
	global_load_dwordx4 v[0:3], v[0:1], off
	v_mad_u64_u32 v[4:5], s[14:15], v8, s40, v[16:17]
	v_mad_i32_i24 v5, v9, s40, v5
	global_load_dwordx4 v[4:7], v[4:5], off
	ds_read_b128 v[26:29], v230
	ds_read2_b32 v[12:13], v210 offset0:16 offset1:48
	s_waitcnt vmcnt(6) lgkmcnt(0)
; __device__ __forceinline__ unsigned cvt_pk_bf16(float lo, float hi) { unsigned r; asm volatile("v_cvt_pk_bf16_f32 %0, %1, %2" : "=v"(r) : "v"(lo), "v"(hi)); return r; }
; #define LAS __attribute__((address_space(3)))
; template <bool MERGE> __device__ __forceinline__ void compute_b(LAS unsigned char* lds, const UD& x, unsigned char* ws, unsigned char* dout, int wid, int lane, const u32x4 (&pw)[10], float mx, float lsum) {
;     ...
; #pragma unroll
;             for (int ii = 0; ii < 2; ++ii) {
;                 const int row = (i0 + ii) * 8 + (lane >> 3), ch = lane & 7; const size_t tok = tokb + (size_t)(t0 + row);
;                 const u32x4 v0 = *(const LAS u32x4*)(stg + row * 64 + ch * 8);
;                 const float m0 = wsf[32 + row], l0 = wsf[row];
;                 const float mxx = fmaxf(fmaxf(m0, m1[ii]), m2[ii]);
;                 float w0 = __builtin_amdgcn_exp2f(m0 - mxx) * l0, w1 = __builtin_amdgcn_exp2f(m1[ii] - mxx) * l1[ii], w2 = __builtin_amdgcn_exp2f(m2[ii] - mxx) * l2[ii];
;                 const float rd = 1.0f / (w0 + w1 + w2); w0 *= rd; w1 *= rd; w2 *= rd;
;                 const u32x4 a1 = o1[ii], a2 = o2[ii];
;                 u32x4 w;
;                 w.x = pg8::cvt_pk_bf16(w0 * __uint_as_float(v0.x << 16) + w1 * __uint_as_float(a1.x << 16) + w2 * __uint_as_float(a2.x << 16), w0 * __uint_as_float(v0.x & 0xffff0000u) + w1 * __uint_as_float(a1.x & 0xffff0000u) + w2 * __uint_as_float(a2.x & 0xffff0000u));
;                 w.y = pg8::cvt_pk_bf16(w0 * __uint_as_float(v0.y << 16) + w1 * __uint_as_float(a1.y << 16) + w2 * __uint_as_float(a2.y << 16), w0 * __uint_as_float(v0.y & 0xffff0000u) + w1 * __uint_as_float(a1.y & 0xffff0000u) + w2 * __uint_as_float(a2.y & 0xffff0000u));
;                 w.z = pg8::cvt_pk_bf16(w0 * __uint_as_float(v0.z << 16) + w1 * __uint_as_float(a1.z << 16) + w2 * __uint_as_float(a2.z << 16), w0 * __uint_as_float(v0.z & 0xffff0000u) + w1 * __uint_as_float(a1.z & 0xffff0000u) + w2 * __uint_as_float(a2.z & 0xffff0000u));
;                 w.w = pg8::cvt_pk_bf16(w0 * __uint_as_float(v0.w << 16) + w1 * __uint_as_float(a1.w << 16) + w2 * __uint_as_float(a2.w << 16), w0 * __uint_as_float(v0.w & 0xffff0000u) + w1 * __uint_as_float(a1.w & 0xffff0000u) + w2 * __uint_as_float(a2.w & 0xffff0000u));
;                 *(u32x4*)(MIX + tok * DM + PWD + x.h * HD + ch * 8) = w;
;             }
;         }
;         if (x.h < 4) {
	v_max3_f32 v16, v13, v32, v34
	v_sub_f32_e32 v13, v13, v16
	v_exp_f32_e32 v17, v13
	v_sub_f32_e32 v13, v32, v16
	v_exp_f32_e32 v32, v13
	v_sub_f32_e32 v13, v34, v16
	v_exp_f32_e32 v16, v13
	s_waitcnt vmcnt(5)
	v_lshlrev_b32_e32 v34, 16, v18
	v_and_b32_e32 v37, 0xffff0000, v18
	v_lshlrev_b32_e32 v38, 16, v19
	v_and_b32_e32 v39, 0xffff0000, v19
	v_mov_b32_e32 v18, v35
	v_mov_b32_e32 v19, v12
	v_pk_mul_f32 v[12:13], v[18:19], v[16:17]
	v_mul_f32_e32 v36, v33, v32
	v_fma_f32 v16, v33, v32, v13
	v_add_f32_e32 v16, v12, v16
	v_div_scale_f32 v17, s[14:15], v16, v16, 1.0
	v_rcp_f32_e32 v18, v17
	v_lshlrev_b32_e32 v40, 16, v20
	v_and_b32_e32 v20, 0xffff0000, v20
	v_lshlrev_b32_e32 v41, 16, v21
	v_fma_f32 v19, -v17, v18, 1.0
	v_fmac_f32_e32 v18, v19, v18
	v_div_scale_f32 v19, vcc, 1.0, v16, 1.0
	v_mul_f32_e32 v32, v19, v18
	v_fma_f32 v33, -v17, v32, v19
	v_fmac_f32_e32 v32, v33, v18
	v_fma_f32 v17, -v17, v32, v19
	v_div_fmas_f32 v17, v17, v18, v32
	v_div_fixup_f32 v16, v17, v16, 1.0
	v_mul_f32_e32 v32, v36, v16
	v_pk_mul_f32 v[12:13], v[12:13], v[16:17] op_sel_hi:[1,0]
	s_waitcnt vmcnt(4)
	v_lshlrev_b32_e32 v16, 16, v22
	v_lshlrev_b32_e32 v17, 16, v26
	v_pk_mul_f32 v[16:17], v[12:13], v[16:17]
	v_lshlrev_b32_e32 v19, 16, v27
	v_fma_f32 v17, v32, v34, v17
	v_add_f32_e32 v18, v16, v17
	v_and_b32_e32 v17, 0xffff0000, v26
	v_and_b32_e32 v16, 0xffff0000, v22
	v_pk_mul_f32 v[16:17], v[12:13], v[16:17]
	s_waitcnt vmcnt(1)
	v_and_b32_e32 v26, 0xffff0000, v2
	v_fma_f32 v17, v32, v37, v17
	v_add_f32_e32 v16, v16, v17
	v_cvt_pk_bf16_f32 v16, v18, v16
	v_lshlrev_b32_e32 v18, 16, v23
	v_pk_mul_f32 v[18:19], v[12:13], v[18:19]
	s_nop 0
	v_fma_f32 v17, v32, v38, v19
	v_add_f32_e32 v17, v18, v17
	v_and_b32_e32 v19, 0xffff0000, v27
	v_and_b32_e32 v18, 0xffff0000, v23
	v_pk_mul_f32 v[18:19], v[12:13], v[18:19]
	v_lshlrev_b32_e32 v23, 16, v29
	v_fma_f32 v19, v32, v39, v19
	v_add_f32_e32 v18, v18, v19
	v_cvt_pk_bf16_f32 v17, v17, v18
	v_lshlrev_b32_e32 v18, 16, v24
	v_lshlrev_b32_e32 v19, 16, v28
	v_pk_mul_f32 v[18:19], v[12:13], v[18:19]
	v_lshlrev_b32_e32 v27, 16, v3
	v_fma_f32 v19, v32, v40, v19
	v_add_f32_e32 v22, v18, v19
	v_and_b32_e32 v19, 0xffff0000, v28
	v_and_b32_e32 v18, 0xffff0000, v24
	v_pk_mul_f32 v[18:19], v[12:13], v[18:19]
	v_and_b32_e32 v24, 0xffff0000, v1
	v_fma_f32 v19, v32, v20, v19
	v_add_f32_e32 v18, v18, v19
	v_cvt_pk_bf16_f32 v18, v22, v18
	v_lshlrev_b32_e32 v22, 16, v25
	v_pk_mul_f32 v[22:23], v[12:13], v[22:23]
	v_and_b32_e32 v20, 0xffff0000, v25
	v_fma_f32 v19, v32, v41, v23
	v_add_f32_e32 v19, v22, v19
	v_and_b32_e32 v22, 0xffff0000, v21
	v_and_b32_e32 v21, 0xffff0000, v29
	v_pk_mul_f32 v[12:13], v[12:13], v[20:21]
	v_lshlrev_b32_e32 v23, 16, v1
	v_fma_f32 v13, v32, v22, v13
	v_add_f32_e32 v12, v12, v13
	v_cvt_pk_bf16_f32 v19, v19, v12
	v_lshlrev_b64 v[12:13], 11, v[30:31]
	v_lshl_add_u64 v[12:13], s[84:85], 0, v[12:13]
	v_lshl_add_u64 v[12:13], v[12:13], 0, s[16:17]
	v_lshl_add_u64 v[12:13], v[12:13], 0, v[144:145]
	global_store_dwordx4 v[12:13], v[16:19], off offset:512
	ds_read_b128 v[16:19], v231
	ds_read2_b32 v[12:13], v210 offset0:24 offset1:56
	v_and_b32_e32 v22, 0xffff0000, v0
	v_lshlrev_b32_e32 v25, 16, v2
	s_waitcnt lgkmcnt(0)
	v_max3_f32 v20, v13, v10, v14
	v_sub_f32_e32 v13, v13, v20
	v_sub_f32_e32 v14, v14, v20
	v_exp_f32_e32 v21, v13
	v_sub_f32_e32 v10, v10, v20
	v_exp_f32_e32 v20, v14
	v_exp_f32_e32 v10, v10
	v_lshlrev_b32_e32 v14, 16, v0
	v_mov_b32_e32 v0, v15
	v_mov_b32_e32 v1, v12
	v_pk_mul_f32 v[0:1], v[0:1], v[20:21]
	v_mul_f32_e32 v13, v11, v10
	v_fma_f32 v2, v11, v10, v1
	v_add_f32_e32 v2, v0, v2
	v_div_scale_f32 v10, s[14:15], v2, v2, 1.0
	v_rcp_f32_e32 v11, v10
	s_nop 0
	v_fma_f32 v12, -v10, v11, 1.0
	v_fmac_f32_e32 v11, v12, v11
	v_div_scale_f32 v12, vcc, 1.0, v2, 1.0
	v_mul_f32_e32 v15, v12, v11
	v_fma_f32 v20, -v10, v15, v12
	v_fmac_f32_e32 v15, v20, v11
	v_fma_f32 v10, -v10, v15, v12
	v_div_fmas_f32 v10, v10, v11, v15
	v_div_fixup_f32 v2, v10, v2, 1.0
	v_pk_mul_f32 v[10:11], v[0:1], v[2:3] op_sel_hi:[1,0]
	s_waitcnt vmcnt(1)
	v_lshlrev_b32_e32 v0, 16, v4
	v_lshlrev_b32_e32 v1, 16, v16
	v_mul_f32_e32 v15, v13, v2
	v_pk_mul_f32 v[0:1], v[10:11], v[0:1]
	v_lshlrev_b32_e32 v12, 16, v5
	v_fma_f32 v1, v15, v14, v1
	v_add_f32_e32 v2, v0, v1
	v_and_b32_e32 v1, 0xffff0000, v16
	v_and_b32_e32 v0, 0xffff0000, v4
	v_pk_mul_f32 v[0:1], v[10:11], v[0:1]
	v_lshlrev_b32_e32 v13, 16, v17
	v_fma_f32 v1, v15, v22, v1
	v_pk_mul_f32 v[12:13], v[10:11], v[12:13]
	v_add_f32_e32 v0, v0, v1
	v_fma_f32 v1, v15, v23, v13
	v_add_f32_e32 v1, v12, v1
	v_and_b32_e32 v13, 0xffff0000, v17
	v_and_b32_e32 v12, 0xffff0000, v5
	v_pk_mul_f32 v[4:5], v[10:11], v[12:13]
	v_cvt_pk_bf16_f32 v0, v2, v0
	v_and_b32_e32 v3, 0xffff0000, v3
	v_fma_f32 v2, v15, v24, v5
	v_add_f32_e32 v2, v4, v2
	v_lshlrev_b32_e32 v4, 16, v6
	v_lshlrev_b32_e32 v5, 16, v18
	v_pk_mul_f32 v[4:5], v[10:11], v[4:5]
	v_cvt_pk_bf16_f32 v1, v1, v2
	s_nop 0
	v_fma_f32 v2, v15, v25, v5
	v_add_f32_e32 v2, v4, v2
	v_and_b32_e32 v5, 0xffff0000, v18
	v_and_b32_e32 v4, 0xffff0000, v6
	v_pk_mul_f32 v[4:5], v[10:11], v[4:5]
	s_nop 0
	v_fma_f32 v5, v15, v26, v5
	v_add_f32_e32 v4, v4, v5
	v_cvt_pk_bf16_f32 v2, v2, v4
	v_lshlrev_b32_e32 v4, 16, v7
	v_lshlrev_b32_e32 v5, 16, v19
	v_pk_mul_f32 v[4:5], v[10:11], v[4:5]
	s_nop 0
	v_fma_f32 v5, v15, v27, v5
	v_add_f32_e32 v6, v4, v5
	v_and_b32_e32 v5, 0xffff0000, v19
	v_and_b32_e32 v4, 0xffff0000, v7
	v_pk_mul_f32 v[4:5], v[10:11], v[4:5]
	s_nop 0
	v_fma_f32 v3, v15, v3, v5
	v_add_f32_e32 v3, v4, v3
	v_lshlrev_b64 v[4:5], 11, v[8:9]
	v_lshl_add_u64 v[4:5], s[84:85], 0, v[4:5]
	v_lshl_add_u64 v[4:5], v[4:5], 0, s[16:17]
	v_lshl_add_u64 v[4:5], v[4:5], 0, v[144:145]
	v_cvt_pk_bf16_f32 v3, v6, v3
	global_store_dwordx4 v[4:5], v[0:3], off offset:512
	s_cbranch_scc1 .LBB0_902
; template <bool MERGE> __device__ __forceinline__ void compute_b(LAS unsigned char* lds, const UD& x, unsigned char* ws, unsigned char* dout, int wid, int lane, const u32x4 (&pw)[10], float mx, float lsum) {
;     ...
;         if (x.h < 4) {
;             const int g = x.h, hw = 1 << g;
;             const bf16_t* VP = (const bf16_t*)(ws + off_vp(x.b));
; #pragma unroll 1
;             for (int p = 0; p < 8; ++p) {
;                 const int s = t0 + 4 * p + (lane >> 4);
;                 const bf16_t* base = VP + tokb * PWD + g * 64 + 4 * (lane & 15);
;                 float s0 = 0.f, s1 = 0.f, s2 = 0.f, s3 = 0.f; int cnt = 0;
;                 const u32x2 me = *(const u32x2*)(base + (size_t)s * PWD);
	s_bfe_u32 s14, s45, 0x30008
	s_lshl_b32 s18, s14, 17
	s_lshl_b32 s19, s14, 8
	s_lshl_b32 s20, -1, s22
	s_mul_i32 s15, s0, 0xa00000
	v_readlane_b32 s24, v252, 1
	s_mul_hi_i32 s14, s0, 0xa00000
	v_readlane_b32 s25, v252, 2
	s_add_u32 s21, s24, s15
	s_addc_u32 s23, s25, s14
	s_lshl_b64 s[14:15], s[0:1], 20
	s_add_u32 s14, s21, s14
	s_addc_u32 s15, s23, s15
	s_add_u32 s14, s14, s16
	s_addc_u32 s15, s15, s17
	v_add_u32_e32 v0, s19, v212
	s_cmp_lg_u32 s22, 0
	v_ashrrev_i32_e32 v1, 31, v0
	v_mov_b32_e32 v147, v81
	s_cselect_b64 s[46:47], -1, 0
	s_cmp_gt_u32 s22, 1
	v_lshlrev_b64 v[4:5], 11, v[0:1]
	v_lshlrev_b64 v[6:7], 9, v[0:1]
	v_lshl_add_u64 v[0:1], s[14:15], 0, v[146:147]
	s_mov_b64 s[14:15], 0xc400000
	s_cselect_b64 s[54:55], -1, 0
	s_cmp_gt_u32 s22, 2
	v_lshl_add_u64 v[0:1], v[0:1], 0, s[14:15]
	s_cselect_b64 s[56:57], -1, 0
	s_lshl_b32 s14, s20, 9
	s_add_i32 s14, s14, s18
	v_add_u32_e32 v2, s14, v211
	s_add_i32 s19, s19, s20
	s_lshl_b64 s[14:15], s[0:1], 22
	s_add_u32 s14, s16, s14
	s_addc_u32 s15, s17, s15
	s_mul_hi_i32 s1, s0, 0xb00000
	s_mul_i32 s0, s0, 0xb00000
	s_add_u32 s0, s16, s0
	s_addc_u32 s1, s17, s1
	v_lshl_add_u64 v[4:5], s[14:15], 0, v[4:5]
	v_lshl_add_u64 v[6:7], s[0:1], 0, v[6:7]
	v_add_u32_e32 v3, s19, v213
	v_lshl_add_u64 v[4:5], v[138:139], 0, v[4:5]
	v_lshl_add_u64 v[6:7], v[140:141], 0, v[6:7]
	s_mov_b64 s[58:59], 0
	v_mbcnt_lo_u32_b32 v232, -1, 0
	v_mbcnt_hi_u32_b32 v232, -1, v232
	v_lshrrev_b32_e32 v233, 3, v232
	v_lshrrev_b32_e32 v234, 4, v232
	v_sub_u32_e32 v233, v233, v234
	v_and_b32_e32 v234, 7, v232
	v_and_b32_e32 v235, 15, v232
	v_lshlrev_b32_e32 v234, 4, v234
	v_lshlrev_b32_e32 v235, 3, v235
	v_sub_u32_e32 v234, v234, v235
	v_lshl_add_u32 v235, v233, 9, v234
	v_lshl_add_u32 v233, v233, 11, v234
	v_ashrrev_i32_e32 v234, 31, v235
	v_add_co_u32_e32 v76, vcc, v6, v235
	v_addc_co_u32_e32 v77, vcc, v7, v234, vcc
	v_ashrrev_i32_e32 v234, 31, v233
	v_add_co_u32_e32 v78, vcc, v4, v233
	v_addc_co_u32_e32 v79, vcc, v5, v234, vcc
	v_readfirstlane_b32 s98, v3
	s_sub_i32 s98, s98, s20
	s_add_i32 s98, s98, -15
	s_mov_b32 s99, 0
	s_mov_b32 s100, 4
	s_mov_b32 s101, 0
	s_cmp_eq_u32 s98, 0
	s_cbranch_scc0 .Lpl_chk_hi
	s_mov_b32 s99, 1
	s_movk_i32 s101, 0x1000
	s_branch .LBB0_944
.Lpl_chk_hi:
	s_cmpk_eq_u32 s98, 0x7e0
	s_cbranch_scc0 .Lpl_fast
	s_mov_b32 s100, 3
	s_movk_i32 s58, 0x3000
	s_movk_i32 s101, 0x4000
	v_add_u32_e32 v3, 24, v3
	v_add_co_u32_e32 v4, vcc, 0xc000, v4
	v_addc_co_u32_e32 v5, vcc, 0, v5, vcc
	s_branch .LBB0_944

; __device__ __forceinline__ unsigned cvt_pk_bf16(float lo, float hi) { unsigned r; asm volatile("v_cvt_pk_bf16_f32 %0, %1, %2" : "=v"(r) : "v"(lo), "v"(hi)); return r; }
; template <bool MERGE> __device__ __forceinline__ void compute_b(LAS unsigned char* lds, const UD& x, unsigned char* ws, unsigned char* dout, int wid, int lane, const u32x4 (&pw)[10], float mx, float lsum) {
;     ...
;                 const float rc = 1.0f / (float)cnt;
;                 u32x2 w2; w2.x = pg8::cvt_pk_bf16(s0 * rc - __uint_as_float(me.x << 16), s1 * rc - __uint_as_float(me.x & 0xffff0000u)); w2.y = pg8::cvt_pk_bf16(s2 * rc - __uint_as_float(me.y << 16), s3 * rc - __uint_as_float(me.y & 0xffff0000u));
;                 *(u32x2*)(MIX + (tokb + (size_t)s) * DM + g * 64 + 4 * (lane & 15)) = w2;
;             }
.LBB0_943:
	v_cvt_f32_u32_e32 v14, v30
	s_add_u32 s58, s58, 0x800
	s_addc_u32 s59, s59, 0
	v_add_u32_e32 v3, 4, v3
	v_div_scale_f32 v15, s[0:1], v14, v14, 1.0
	v_rcp_f32_e32 v16, v15
	s_cmp_lg_u32 s58, s101
	v_fma_f32 v17, -v15, v16, 1.0
	v_fmac_f32_e32 v16, v17, v16
	v_div_scale_f32 v17, vcc, 1.0, v14, 1.0
	v_mul_f32_e32 v18, v17, v16
	v_fma_f32 v19, -v15, v18, v17
	v_fmac_f32_e32 v18, v19, v16
	v_fma_f32 v15, -v15, v18, v17
	v_div_fmas_f32 v15, v15, v16, v18
	v_div_fixup_f32 v14, v15, v14, 1.0
	v_lshlrev_b32_e32 v15, 16, v8
	v_and_b32_e32 v8, 0xffff0000, v8
	v_fma_f32 v10, v10, v14, -v15
	v_fma_f32 v8, v11, v14, -v8
	v_cvt_pk_bf16_f32 v8, v10, v8
	v_lshlrev_b32_e32 v10, 16, v9
	v_and_b32_e32 v9, 0xffff0000, v9
	v_fma_f32 v9, v13, v14, -v9
	v_fma_f32 v10, v12, v14, -v10
	v_cvt_pk_bf16_f32 v9, v10, v9
	global_store_dwordx2 v[4:5], v[8:9], off
	v_lshl_add_u64 v[4:5], v[4:5], 0, s[86:87]
	s_cbranch_scc0 .Lpl_fast

; template <bool MERGE> __device__ __forceinline__ void compute_b(LAS unsigned char* lds, const UD& x, unsigned char* ws, unsigned char* dout, int wid, int lane, const u32x4 (&pw)[10], float mx, float lsum) {
;     ...
;             for (int p = 0; p < 8; ++p) {
;                 const int s = t0 + 4 * p + (lane >> 4);
;                 const bf16_t* base = VP + tokb * PWD + g * 64 + 4 * (lane & 15);
;                 float s0 = 0.f, s1 = 0.f, s2 = 0.f, s3 = 0.f; int cnt = 0;
;                 const u32x2 me = *(const u32x2*)(base + (size_t)s * PWD);
; #pragma unroll
;                 for (int j0 = 0; j0 < 16; j0 += 8) {
;                     if (j0 < 2 * hw) {
;                         u32x2 vv[8];
; #pragma unroll
;                         for (int jj = 0; jj < 8; ++jj) { const int j = s - hw + j0 + jj; const bool ok = (j0 + jj < 2 * hw) && (j >= 0) && (j < SEQ);
;                             vv[jj] = (u32x2){0u, 0u}; if (ok) vv[jj] = *(const u32x2*)(base + (size_t)j * PWD); cnt += ok ? 1 : 0; }
; #pragma unroll
;                         for (int jj = 0; jj < 8; ++jj) { s0 += __uint_as_float(vv[jj].x << 16); s1 += __uint_as_float(vv[jj].x & 0xffff0000u); s2 += __uint_as_float(vv[jj].y << 16); s3 += __uint_as_float(vv[jj].y & 0xffff0000u); }
;                     }
;                 }
.Lpl_fast:
	s_cmp_ge_u32 s99, s100
	s_cbranch_scc1 .LBB0_902
	s_lshl_b32 s98, s99, 12
	v_add_co_u32_e32 v76, vcc, s98, v76
	v_addc_co_u32_e32 v77, vcc, 0, v77, vcc
	s_lshl_b32 s98, s99, 14
	v_add_co_u32_e32 v78, vcc, s98, v78
	v_addc_co_u32_e32 v79, vcc, 0, v79, vcc
	s_mov_b32 s101, 0.5
	s_cmp_lg_u64 s[46:47], 0
	s_cselect_b32 s101, 0x3e800000, s101
	s_cmp_lg_u64 s[54:55], 0
	s_cselect_b32 s101, 0x3e000000, s101
	s_cmp_lg_u64 s[56:57], 0
	s_cselect_b32 s101, 0x3d800000, s101
	v_mov_b64_e32 v[12:13], 0
	v_mov_b64_e32 v[14:15], 0
	v_mov_b64_e32 v[16:17], 0
	v_mov_b64_e32 v[18:19], 0
	v_mov_b64_e32 v[20:21], 0
	v_mov_b64_e32 v[22:23], 0
	v_mov_b64_e32 v[24:25], 0
	v_mov_b64_e32 v[26:27], 0
	v_mov_b64_e32 v[28:29], 0
	v_mov_b64_e32 v[30:31], 0
	v_mov_b64_e32 v[32:33], 0
	v_mov_b64_e32 v[34:35], 0
	v_mov_b64_e32 v[36:37], 0
	v_mov_b64_e32 v[38:39], 0
	v_mov_b64_e32 v[40:41], 0
	v_mov_b64_e32 v[42:43], 0
	v_mov_b64_e32 v[44:45], 0
	v_mov_b64_e32 v[46:47], 0
	v_mov_b64_e32 v[48:49], 0
	v_mov_b64_e32 v[50:51], 0
	v_mov_b64_e32 v[52:53], 0
	v_mov_b64_e32 v[54:55], 0
	v_mov_b64_e32 v[56:57], 0
	v_mov_b64_e32 v[58:59], 0
	v_mov_b64_e32 v[60:61], 0
	v_mov_b64_e32 v[62:63], 0
	v_mov_b64_e32 v[64:65], 0
	v_mov_b64_e32 v[66:67], 0
	v_mov_b64_e32 v[68:69], 0
	v_mov_b64_e32 v[70:71], 0
	v_mov_b64_e32 v[72:73], 0
	v_mov_b64_e32 v[74:75], 0
.Lpl_pass:
	global_load_dwordx4 v[8:11], v[76:77], off
	global_load_dwordx4 v[40:43], v[76:77], off offset:-512
	global_load_dwordx4 v[44:47], v[76:77], off
	s_cmp_lg_u64 s[46:47], 0
	s_cbranch_scc0 .Lpl_ld_done
	global_load_dwordx4 v[36:39], v[76:77], off offset:-1024
	global_load_dwordx4 v[48:51], v[76:77], off offset:512
	s_cmp_lg_u64 s[54:55], 0
	s_cbranch_scc0 .Lpl_ld_done
	global_load_dwordx4 v[28:31], v[76:77], off offset:-2048
	global_load_dwordx4 v[32:35], v[76:77], off offset:-1536
	global_load_dwordx4 v[52:55], v[76:77], off offset:1024
	global_load_dwordx4 v[56:59], v[76:77], off offset:1536
	s_cmp_lg_u64 s[56:57], 0
	s_cbranch_scc0 .Lpl_ld_done
	global_load_dwordx4 v[12:15], v[76:77], off offset:-4096
	global_load_dwordx4 v[16:19], v[76:77], off offset:-3584
	global_load_dwordx4 v[20:23], v[76:77], off offset:-3072
	global_load_dwordx4 v[24:27], v[76:77], off offset:-2560
	global_load_dwordx4 v[60:63], v[76:77], off offset:2048
	global_load_dwordx4 v[64:67], v[76:77], off offset:2560
	global_load_dwordx4 v[68:71], v[76:77], off offset:3072
	global_load_dwordx4 v[72:75], v[76:77], off offset:3584
.Lpl_ld_done:
	v_mov_b64_e32 v[242:243], 0
	v_mov_b64_e32 v[244:245], 0
	v_mov_b64_e32 v[246:247], 0
	v_mov_b64_e32 v[248:249], 0
	s_waitcnt vmcnt(0)
	s_cmp_lg_u64 s[56:57], 0
	s_cbranch_scc0 .Lpl_s1
	v_lshlrev_b32_e32 v232, 16, v12
	v_and_b32_e32 v233, 0xffff0000, v12
	v_pk_add_f32 v[242:243], v[242:243], v[232:233]
	v_lshlrev_b32_e32 v234, 16, v13
	v_and_b32_e32 v235, 0xffff0000, v13
	v_pk_add_f32 v[244:245], v[244:245], v[234:235]
	v_lshlrev_b32_e32 v232, 16, v14
	v_and_b32_e32 v233, 0xffff0000, v14
	v_pk_add_f32 v[246:247], v[246:247], v[232:233]
	v_lshlrev_b32_e32 v234, 16, v15
	v_and_b32_e32 v235, 0xffff0000, v15
	v_pk_add_f32 v[248:249], v[248:249], v[234:235]
	v_lshlrev_b32_e32 v232, 16, v16
	v_and_b32_e32 v233, 0xffff0000, v16
	v_pk_add_f32 v[242:243], v[242:243], v[232:233]
	v_lshlrev_b32_e32 v234, 16, v17
	v_and_b32_e32 v235, 0xffff0000, v17
	v_pk_add_f32 v[244:245], v[244:245], v[234:235]
	v_lshlrev_b32_e32 v232, 16, v18
	v_and_b32_e32 v233, 0xffff0000, v18
	v_pk_add_f32 v[246:247], v[246:247], v[232:233]
	v_lshlrev_b32_e32 v234, 16, v19
	v_and_b32_e32 v235, 0xffff0000, v19
	v_pk_add_f32 v[248:249], v[248:249], v[234:235]
	v_lshlrev_b32_e32 v232, 16, v20
	v_and_b32_e32 v233, 0xffff0000, v20
	v_pk_add_f32 v[242:243], v[242:243], v[232:233]
	v_lshlrev_b32_e32 v234, 16, v21
	v_and_b32_e32 v235, 0xffff0000, v21
	v_pk_add_f32 v[244:245], v[244:245], v[234:235]
	v_lshlrev_b32_e32 v232, 16, v22
	v_and_b32_e32 v233, 0xffff0000, v22
	v_pk_add_f32 v[246:247], v[246:247], v[232:233]
	v_lshlrev_b32_e32 v234, 16, v23
	v_and_b32_e32 v235, 0xffff0000, v23
	v_pk_add_f32 v[248:249], v[248:249], v[234:235]
	v_lshlrev_b32_e32 v232, 16, v24
	v_and_b32_e32 v233, 0xffff0000, v24
	v_pk_add_f32 v[242:243], v[242:243], v[232:233]
	v_lshlrev_b32_e32 v234, 16, v25
	v_and_b32_e32 v235, 0xffff0000, v25
	v_pk_add_f32 v[244:245], v[244:245], v[234:235]
	v_lshlrev_b32_e32 v232, 16, v26
	v_and_b32_e32 v233, 0xffff0000, v26
	v_pk_add_f32 v[246:247], v[246:247], v[232:233]
	v_lshlrev_b32_e32 v234, 16, v27
	v_and_b32_e32 v235, 0xffff0000, v27
	v_pk_add_f32 v[248:249], v[248:249], v[234:235]
.Lpl_s1:
	s_cmp_lg_u64 s[54:55], 0
	s_cbranch_scc0 .Lpl_s2
	v_lshlrev_b32_e32 v232, 16, v28
	v_and_b32_e32 v233, 0xffff0000, v28
	v_pk_add_f32 v[242:243], v[242:243], v[232:233]
	v_lshlrev_b32_e32 v234, 16, v29
	v_and_b32_e32 v235, 0xffff0000, v29
	v_pk_add_f32 v[244:245], v[244:245], v[234:235]
	v_lshlrev_b32_e32 v232, 16, v30
	v_and_b32_e32 v233, 0xffff0000, v30
	v_pk_add_f32 v[246:247], v[246:247], v[232:233]
	v_lshlrev_b32_e32 v234, 16, v31
	v_and_b32_e32 v235, 0xffff0000, v31
	v_pk_add_f32 v[248:249], v[248:249], v[234:235]
	v_lshlrev_b32_e32 v232, 16, v32
	v_and_b32_e32 v233, 0xffff0000, v32
	v_pk_add_f32 v[242:243], v[242:243], v[232:233]
	v_lshlrev_b32_e32 v234, 16, v33
	v_and_b32_e32 v235, 0xffff0000, v33
	v_pk_add_f32 v[244:245], v[244:245], v[234:235]
	v_lshlrev_b32_e32 v232, 16, v34
	v_and_b32_e32 v233, 0xffff0000, v34
	v_pk_add_f32 v[246:247], v[246:247], v[232:233]
	v_lshlrev_b32_e32 v234, 16, v35
	v_and_b32_e32 v235, 0xffff0000, v35
	v_pk_add_f32 v[248:249], v[248:249], v[234:235]
; __device__ __forceinline__ unsigned cvt_pk_bf16(float lo, float hi) { unsigned r; asm volatile("v_cvt_pk_bf16_f32 %0, %1, %2" : "=v"(r) : "v"(lo), "v"(hi)); return r; }
; template <bool MERGE> __device__ __forceinline__ void compute_b(LAS unsigned char* lds, const UD& x, unsigned char* ws, unsigned char* dout, int wid, int lane, const u32x4 (&pw)[10], float mx, float lsum) {
;     ...
;                 for (int j0 = 0; j0 < 16; j0 += 8) {
;                     if (j0 < 2 * hw) {
;                         u32x2 vv[8];
; #pragma unroll
;                         for (int jj = 0; jj < 8; ++jj) { const int j = s - hw + j0 + jj; const bool ok = (j0 + jj < 2 * hw) && (j >= 0) && (j < SEQ);
;                             vv[jj] = (u32x2){0u, 0u}; if (ok) vv[jj] = *(const u32x2*)(base + (size_t)j * PWD); cnt += ok ? 1 : 0; }
; #pragma unroll
;                         for (int jj = 0; jj < 8; ++jj) { s0 += __uint_as_float(vv[jj].x << 16); s1 += __uint_as_float(vv[jj].x & 0xffff0000u); s2 += __uint_as_float(vv[jj].y << 16); s3 += __uint_as_float(vv[jj].y & 0xffff0000u); }
;                     }
;                 }
;                 const float rc = 1.0f / (float)cnt;
;                 u32x2 w2; w2.x = pg8::cvt_pk_bf16(s0 * rc - __uint_as_float(me.x << 16), s1 * rc - __uint_as_float(me.x & 0xffff0000u)); w2.y = pg8::cvt_pk_bf16(s2 * rc - __uint_as_float(me.y << 16), s3 * rc - __uint_as_float(me.y & 0xffff0000u));
;                 *(u32x2*)(MIX + (tokb + (size_t)s) * DM + g * 64 + 4 * (lane & 15)) = w2;
.Lpl_s2:
	s_cmp_lg_u64 s[46:47], 0
	s_cbranch_scc0 .Lpl_s3
	v_lshlrev_b32_e32 v232, 16, v36
	v_and_b32_e32 v233, 0xffff0000, v36
	v_pk_add_f32 v[242:243], v[242:243], v[232:233]
	v_lshlrev_b32_e32 v234, 16, v37
	v_and_b32_e32 v235, 0xffff0000, v37
	v_pk_add_f32 v[244:245], v[244:245], v[234:235]
	v_lshlrev_b32_e32 v232, 16, v38
	v_and_b32_e32 v233, 0xffff0000, v38
	v_pk_add_f32 v[246:247], v[246:247], v[232:233]
	v_lshlrev_b32_e32 v234, 16, v39
	v_and_b32_e32 v235, 0xffff0000, v39
	v_pk_add_f32 v[248:249], v[248:249], v[234:235]
.Lpl_s3:
	v_lshlrev_b32_e32 v232, 16, v40
	v_and_b32_e32 v233, 0xffff0000, v40
	v_pk_add_f32 v[242:243], v[242:243], v[232:233]
	v_lshlrev_b32_e32 v234, 16, v41
	v_and_b32_e32 v235, 0xffff0000, v41
	v_pk_add_f32 v[244:245], v[244:245], v[234:235]
	v_lshlrev_b32_e32 v232, 16, v42
	v_and_b32_e32 v233, 0xffff0000, v42
	v_pk_add_f32 v[246:247], v[246:247], v[232:233]
	v_lshlrev_b32_e32 v234, 16, v43
	v_and_b32_e32 v235, 0xffff0000, v43
	v_pk_add_f32 v[248:249], v[248:249], v[234:235]
	v_lshlrev_b32_e32 v232, 16, v44
	v_and_b32_e32 v233, 0xffff0000, v44
	v_pk_add_f32 v[242:243], v[242:243], v[232:233]
	v_lshlrev_b32_e32 v234, 16, v45
	v_and_b32_e32 v235, 0xffff0000, v45
	v_pk_add_f32 v[244:245], v[244:245], v[234:235]
	v_lshlrev_b32_e32 v232, 16, v46
	v_and_b32_e32 v233, 0xffff0000, v46
	v_pk_add_f32 v[246:247], v[246:247], v[232:233]
	v_lshlrev_b32_e32 v234, 16, v47
	v_and_b32_e32 v235, 0xffff0000, v47
	v_pk_add_f32 v[248:249], v[248:249], v[234:235]
	s_cmp_lg_u64 s[46:47], 0
	s_cbranch_scc0 .Lpl_s6
	v_lshlrev_b32_e32 v232, 16, v48
	v_and_b32_e32 v233, 0xffff0000, v48
	v_pk_add_f32 v[242:243], v[242:243], v[232:233]
	v_lshlrev_b32_e32 v234, 16, v49
	v_and_b32_e32 v235, 0xffff0000, v49
	v_pk_add_f32 v[244:245], v[244:245], v[234:235]
	v_lshlrev_b32_e32 v232, 16, v50
	v_and_b32_e32 v233, 0xffff0000, v50
	v_pk_add_f32 v[246:247], v[246:247], v[232:233]
	v_lshlrev_b32_e32 v234, 16, v51
	v_and_b32_e32 v235, 0xffff0000, v51
	v_pk_add_f32 v[248:249], v[248:249], v[234:235]
	s_cmp_lg_u64 s[54:55], 0
	s_cbranch_scc0 .Lpl_s6
	v_lshlrev_b32_e32 v232, 16, v52
	v_and_b32_e32 v233, 0xffff0000, v52
	v_pk_add_f32 v[242:243], v[242:243], v[232:233]
	v_lshlrev_b32_e32 v234, 16, v53
	v_and_b32_e32 v235, 0xffff0000, v53
	v_pk_add_f32 v[244:245], v[244:245], v[234:235]
	v_lshlrev_b32_e32 v232, 16, v54
	v_and_b32_e32 v233, 0xffff0000, v54
	v_pk_add_f32 v[246:247], v[246:247], v[232:233]
	v_lshlrev_b32_e32 v234, 16, v55
	v_and_b32_e32 v235, 0xffff0000, v55
	v_pk_add_f32 v[248:249], v[248:249], v[234:235]
	v_lshlrev_b32_e32 v232, 16, v56
	v_and_b32_e32 v233, 0xffff0000, v56
	v_pk_add_f32 v[242:243], v[242:243], v[232:233]
	v_lshlrev_b32_e32 v234, 16, v57
	v_and_b32_e32 v235, 0xffff0000, v57
	v_pk_add_f32 v[244:245], v[244:245], v[234:235]
	v_lshlrev_b32_e32 v232, 16, v58
	v_and_b32_e32 v233, 0xffff0000, v58
	v_pk_add_f32 v[246:247], v[246:247], v[232:233]
	v_lshlrev_b32_e32 v234, 16, v59
	v_and_b32_e32 v235, 0xffff0000, v59
	v_pk_add_f32 v[248:249], v[248:249], v[234:235]
	s_cmp_lg_u64 s[56:57], 0
	s_cbranch_scc0 .Lpl_s6
	v_lshlrev_b32_e32 v232, 16, v60
	v_and_b32_e32 v233, 0xffff0000, v60
	v_pk_add_f32 v[242:243], v[242:243], v[232:233]
	v_lshlrev_b32_e32 v234, 16, v61
	v_and_b32_e32 v235, 0xffff0000, v61
	v_pk_add_f32 v[244:245], v[244:245], v[234:235]
	v_lshlrev_b32_e32 v232, 16, v62
	v_and_b32_e32 v233, 0xffff0000, v62
	v_pk_add_f32 v[246:247], v[246:247], v[232:233]
	v_lshlrev_b32_e32 v234, 16, v63
	v_and_b32_e32 v235, 0xffff0000, v63
	v_pk_add_f32 v[248:249], v[248:249], v[234:235]
	v_lshlrev_b32_e32 v232, 16, v64
	v_and_b32_e32 v233, 0xffff0000, v64
	v_pk_add_f32 v[242:243], v[242:243], v[232:233]
	v_lshlrev_b32_e32 v234, 16, v65
	v_and_b32_e32 v235, 0xffff0000, v65
	v_pk_add_f32 v[244:245], v[244:245], v[234:235]
	v_lshlrev_b32_e32 v232, 16, v66
	v_and_b32_e32 v233, 0xffff0000, v66
	v_pk_add_f32 v[246:247], v[246:247], v[232:233]
	v_lshlrev_b32_e32 v234, 16, v67
	v_and_b32_e32 v235, 0xffff0000, v67
	v_pk_add_f32 v[248:249], v[248:249], v[234:235]
	v_lshlrev_b32_e32 v232, 16, v68
	v_and_b32_e32 v233, 0xffff0000, v68
	v_pk_add_f32 v[242:243], v[242:243], v[232:233]
	v_lshlrev_b32_e32 v234, 16, v69
	v_and_b32_e32 v235, 0xffff0000, v69
	v_pk_add_f32 v[244:245], v[244:245], v[234:235]
	v_lshlrev_b32_e32 v232, 16, v70
	v_and_b32_e32 v233, 0xffff0000, v70
	v_pk_add_f32 v[246:247], v[246:247], v[232:233]
	v_lshlrev_b32_e32 v234, 16, v71
	v_and_b32_e32 v235, 0xffff0000, v71
	v_pk_add_f32 v[248:249], v[248:249], v[234:235]
	v_lshlrev_b32_e32 v232, 16, v72
	v_and_b32_e32 v233, 0xffff0000, v72
	v_pk_add_f32 v[242:243], v[242:243], v[232:233]
	v_lshlrev_b32_e32 v234, 16, v73
	v_and_b32_e32 v235, 0xffff0000, v73
	v_pk_add_f32 v[244:245], v[244:245], v[234:235]
	v_lshlrev_b32_e32 v232, 16, v74
	v_and_b32_e32 v233, 0xffff0000, v74
	v_pk_add_f32 v[246:247], v[246:247], v[232:233]
	v_lshlrev_b32_e32 v234, 16, v75
	v_and_b32_e32 v235, 0xffff0000, v75
	v_pk_add_f32 v[248:249], v[248:249], v[234:235]
.Lpl_s6:
	v_lshlrev_b32_e32 v232, 16, v8
	v_and_b32_e32 v233, 0xffff0000, v8
	v_fma_f32 v234, v242, s101, -v232
	v_fma_f32 v235, v243, s101, -v233
	v_cvt_pk_bf16_f32 v196, v234, v235
	v_lshlrev_b32_e32 v232, 16, v9
	v_and_b32_e32 v233, 0xffff0000, v9
	v_fma_f32 v234, v244, s101, -v232
	v_fma_f32 v235, v245, s101, -v233
	v_cvt_pk_bf16_f32 v197, v234, v235
	v_lshlrev_b32_e32 v232, 16, v10
	v_and_b32_e32 v233, 0xffff0000, v10
	v_fma_f32 v234, v246, s101, -v232
	v_fma_f32 v235, v247, s101, -v233
	v_cvt_pk_bf16_f32 v198, v234, v235
	v_lshlrev_b32_e32 v232, 16, v11
	v_and_b32_e32 v233, 0xffff0000, v11
	v_fma_f32 v234, v248, s101, -v232
	v_fma_f32 v235, v249, s101, -v233
	v_cvt_pk_bf16_f32 v199, v234, v235
	global_store_dwordx4 v[78:79], v[196:199], off
	v_add_co_u32_e32 v76, vcc, 0x1000, v76
	v_addc_co_u32_e32 v77, vcc, 0, v77, vcc
	v_add_co_u32_e32 v78, vcc, 0x4000, v78
	v_addc_co_u32_e32 v79, vcc, 0, v79, vcc
	s_add_i32 s99, s99, 1
	s_cmp_lt_u32 s99, s100
	s_cbranch_scc1 .Lpl_pass
	s_branch .LBB0_902
